# final RMSNorm phase: streaming (nt) loads of the residual rows and nt stores of the f32 output, on top of the cached-Q XQ epilogue
# baseline (speedup 1.0000x reference)
; __global__ void __launch_bounds__(NWAVES * 64, 2) trunk_fwd(Args args) {
;     ...
;             const f32x4* gr = (const f32x4*)(ARGIN(I_FING) + lane * 8);
;             const f32x4 g0 = gr[0], g1 = gr[1], g2 = gr[128], g3 = gr[129];
;             for (int row0 = gw; row0 < M; row0 += 2 * NGW) {
;                 v4u h0[2], h1[2];
; #pragma unroll
;                 for (int k = 0; k < 2; ++k) { const bf16* hp = HB + (size_t)(row0 + k * NGW) * DM + lane * 8; h0[k] = *(const v4u*)(hp); h1[k] = *(const v4u*)(hp + 512); }
.LBB0_594:
	s_cmp_gt_i32 s60, 0xffff
	s_cbranch_scc1 .LBB0_597
	s_load_dwordx2 s[4:5], s[62:63], 0x38
	v_lshlrev_b32_e32 v0, 5, v216
	v_lshlrev_b32_e32 v18, 4, v216
	v_mov_b32_e32 v19, v1
	v_lshl_add_u64 v[28:29], s[16:17], 0, v[0:1]
	v_lshl_add_u64 v[26:27], s[58:59], 0, v[18:19]
	s_waitcnt vmcnt(0) lgkmcnt(0)
	global_load_dwordx4 v[6:9], v0, s[4:5]
	global_load_dwordx4 v[2:5], v0, s[4:5] offset:16
	global_load_dwordx4 v[14:17], v0, s[4:5] offset:2048
	global_load_dwordx4 v[10:13], v0, s[4:5] offset:2064
	s_add_i32 s20, s60, 0
	s_lshl_b32 s20, s20, 11
	s_mov_b32 s21, 0
	v_lshl_add_u64 v[132:133], v[26:27], 0, s[20:21]
	global_load_dwordx4 v[32:35], v[132:133], off nt
	global_load_dwordx4 v[36:39], v[132:133], off offset:1024 nt
	s_add_i32 s20, s60, 2048
	s_lshl_b32 s20, s20, 11
	s_mov_b32 s21, 0
	v_lshl_add_u64 v[132:133], v[26:27], 0, s[20:21]
	global_load_dwordx4 v[40:43], v[132:133], off nt
	global_load_dwordx4 v[44:47], v[132:133], off offset:1024 nt
	s_add_i32 s20, s60, 4096
	s_lshl_b32 s20, s20, 11
	s_mov_b32 s21, 0
	v_lshl_add_u64 v[132:133], v[26:27], 0, s[20:21]
	global_load_dwordx4 v[48:51], v[132:133], off nt
	global_load_dwordx4 v[52:55], v[132:133], off offset:1024 nt
	s_add_i32 s20, s60, 6144
	s_lshl_b32 s20, s20, 11
	s_mov_b32 s21, 0
	v_lshl_add_u64 v[132:133], v[26:27], 0, s[20:21]
	global_load_dwordx4 v[56:59], v[132:133], off nt
	global_load_dwordx4 v[60:63], v[132:133], off offset:1024 nt
	s_add_i32 s22, s60, 0x2000
	s_add_i32 s20, s22, 0
	s_lshl_b32 s20, s20, 11
	s_mov_b32 s21, 0
	v_lshl_add_u64 v[132:133], v[26:27], 0, s[20:21]
	global_load_dwordx4 v[64:67], v[132:133], off nt
	global_load_dwordx4 v[68:71], v[132:133], off offset:1024 nt
	s_add_i32 s20, s22, 2048
	s_lshl_b32 s20, s20, 11
	s_mov_b32 s21, 0
	v_lshl_add_u64 v[132:133], v[26:27], 0, s[20:21]
	global_load_dwordx4 v[72:75], v[132:133], off nt
	global_load_dwordx4 v[76:79], v[132:133], off offset:1024 nt
	s_add_i32 s20, s22, 4096
	s_lshl_b32 s20, s20, 11
	s_mov_b32 s21, 0
	v_lshl_add_u64 v[132:133], v[26:27], 0, s[20:21]
	global_load_dwordx4 v[80:83], v[132:133], off nt
	global_load_dwordx4 v[84:87], v[132:133], off offset:1024 nt
	s_add_i32 s20, s22, 6144
	s_lshl_b32 s20, s20, 11
	s_mov_b32 s21, 0
	v_lshl_add_u64 v[132:133], v[26:27], 0, s[20:21]
	global_load_dwordx4 v[88:91], v[132:133], off nt
	global_load_dwordx4 v[92:95], v[132:133], off offset:1024 nt
	s_mov_b32 s23, 1

; __device__ __forceinline__ float bf_lo(unsigned w) { return __uint_as_float(w << 16); }
; __device__ __forceinline__ float bf_hi(unsigned w) { return __uint_as_float(w & 0xffff0000u); }
; __global__ void __launch_bounds__(NWAVES * 64, 2) trunk_fwd(Args args) {
;     ...
;                 for (int k = 0; k < 2; ++k) { float* op = out + (size_t)(row0 + k * NGW) * DM + lane * 8;
;                     const f32x4 a0 = {bf_lo(h0[k].x), bf_hi(h0[k].x), bf_lo(h0[k].y), bf_hi(h0[k].y)}, a1 = {bf_lo(h0[k].z), bf_hi(h0[k].z), bf_lo(h0[k].w), bf_hi(h0[k].w)};
;                     const f32x4 a2 = {bf_lo(h1[k].x), bf_hi(h1[k].x), bf_lo(h1[k].y), bf_hi(h1[k].y)}, a3 = {bf_lo(h1[k].z), bf_hi(h1[k].z), bf_lo(h1[k].w), bf_hi(h1[k].w)};
;                     float sq = ((a0[0] * a0[0] + a0[1] * a0[1]) + (a0[2] * a0[2] + a0[3] * a0[3])) + ((a1[0] * a1[0] + a1[1] * a1[1]) + (a1[2] * a1[2] + a1[3] * a1[3]))
;                              + ((a2[0] * a2[0] + a2[1] * a2[1]) + (a2[2] * a2[2] + a2[3] * a2[3])) + ((a3[0] * a3[0] + a3[1] * a3[1]) + (a3[2] * a3[2] + a3[3] * a3[3]));
;                     const float r = __builtin_amdgcn_rsqf(wave_sum(sq) * (1.f / DM) + EPS);
;                     *(f32x4*)(op) = a0 * r * g0; *(f32x4*)(op + 4) = a1 * r * g1; *(f32x4*)(op + 512) = a2 * r * g2; *(f32x4*)(op + 516) = a3 * r * g3; }
.Lfin_wad:
	s_mov_b32 s23, 0
	v_lshlrev_b32_e32 v96, 16, v32
	v_and_b32_e32 v97, 0xffff0000, v32
	v_lshlrev_b32_e32 v98, 16, v33
	v_and_b32_e32 v99, 0xffff0000, v33
	v_lshlrev_b32_e32 v100, 16, v34
	v_and_b32_e32 v101, 0xffff0000, v34
	v_lshlrev_b32_e32 v102, 16, v35
	v_and_b32_e32 v103, 0xffff0000, v35
	v_lshlrev_b32_e32 v104, 16, v36
	v_and_b32_e32 v105, 0xffff0000, v36
	v_lshlrev_b32_e32 v106, 16, v37
	v_and_b32_e32 v107, 0xffff0000, v37
	v_lshlrev_b32_e32 v108, 16, v38
	v_and_b32_e32 v109, 0xffff0000, v38
	v_lshlrev_b32_e32 v110, 16, v39
	v_and_b32_e32 v111, 0xffff0000, v39
	v_pk_mul_f32 v[128:129], v[96:97], v[96:97]
	v_pk_fma_f32 v[128:129], v[98:99], v[98:99], v[128:129]
	v_pk_fma_f32 v[128:129], v[100:101], v[100:101], v[128:129]
	v_pk_fma_f32 v[128:129], v[102:103], v[102:103], v[128:129]
	v_pk_fma_f32 v[128:129], v[104:105], v[104:105], v[128:129]
	v_pk_fma_f32 v[128:129], v[106:107], v[106:107], v[128:129]
	v_pk_fma_f32 v[128:129], v[108:109], v[108:109], v[128:129]
	v_pk_fma_f32 v[128:129], v[110:111], v[110:111], v[128:129]
	v_add_f32_e32 v128, v128, v129
	s_nop 1
	v_add_f32_dpp v128, v128, v128 quad_perm:[1,0,3,2] row_mask:0xf bank_mask:0xf
	s_nop 1
	v_add_f32_dpp v128, v128, v128 quad_perm:[2,3,0,1] row_mask:0xf bank_mask:0xf
	s_nop 1
	v_add_f32_dpp v128, v128, v128 row_half_mirror row_mask:0xf bank_mask:0xf
	s_nop 1
	v_add_f32_dpp v128, v128, v128 row_mirror row_mask:0xf bank_mask:0xf
	s_nop 1
	v_readlane_b32 s6, v128, 0
	v_readlane_b32 s7, v128, 16
	v_readlane_b32 s8, v128, 32
	v_readlane_b32 s9, v128, 48
	s_nop 1
	v_mov_b32_e32 v130, s6
	v_add_f32_e32 v130, s7, v130
	v_add_f32_e32 v130, s8, v130
	v_add_f32_e32 v130, s9, v130
	v_fmamk_f32 v130, v130, 0x3a800000, v207
	v_rsq_f32_e32 v130, v130
	s_add_i32 s20, s60, 0
	s_lshl_b32 s20, s20, 12
	s_mov_b32 s21, 0
	v_lshl_add_u64 v[134:135], v[28:29], 0, s[20:21]
	v_pk_mul_f32 v[96:97], v[96:97], v[130:131] op_sel_hi:[1,0]
	v_pk_mul_f32 v[98:99], v[98:99], v[130:131] op_sel_hi:[1,0]
	v_pk_mul_f32 v[100:101], v[100:101], v[130:131] op_sel_hi:[1,0]
	v_pk_mul_f32 v[102:103], v[102:103], v[130:131] op_sel_hi:[1,0]
	v_pk_mul_f32 v[104:105], v[104:105], v[130:131] op_sel_hi:[1,0]
	v_pk_mul_f32 v[106:107], v[106:107], v[130:131] op_sel_hi:[1,0]
	v_pk_mul_f32 v[108:109], v[108:109], v[130:131] op_sel_hi:[1,0]
	v_pk_mul_f32 v[110:111], v[110:111], v[130:131] op_sel_hi:[1,0]
	v_pk_mul_f32 v[96:97], v[96:97], v[6:7]
	v_pk_mul_f32 v[98:99], v[98:99], v[8:9]
	v_pk_mul_f32 v[100:101], v[100:101], v[2:3]
	v_pk_mul_f32 v[102:103], v[102:103], v[4:5]
	v_pk_mul_f32 v[104:105], v[104:105], v[14:15]
	v_pk_mul_f32 v[106:107], v[106:107], v[16:17]
	v_pk_mul_f32 v[108:109], v[108:109], v[10:11]
	v_pk_mul_f32 v[110:111], v[110:111], v[12:13]
	global_store_dwordx4 v[134:135], v[96:99], off nt
	global_store_dwordx4 v[134:135], v[100:103], off offset:16 nt
	global_store_dwordx4 v[134:135], v[104:107], off offset:2048 nt
	global_store_dwordx4 v[134:135], v[108:111], off offset:2064 nt
	v_lshlrev_b32_e32 v112, 16, v40
	v_and_b32_e32 v113, 0xffff0000, v40
	v_lshlrev_b32_e32 v114, 16, v41
	v_and_b32_e32 v115, 0xffff0000, v41
	v_lshlrev_b32_e32 v116, 16, v42
	v_and_b32_e32 v117, 0xffff0000, v42
	v_lshlrev_b32_e32 v118, 16, v43
	v_and_b32_e32 v119, 0xffff0000, v43
	v_lshlrev_b32_e32 v120, 16, v44
	v_and_b32_e32 v121, 0xffff0000, v44
	v_lshlrev_b32_e32 v122, 16, v45
	v_and_b32_e32 v123, 0xffff0000, v45
	v_lshlrev_b32_e32 v124, 16, v46
	v_and_b32_e32 v125, 0xffff0000, v46
	v_lshlrev_b32_e32 v126, 16, v47
	v_and_b32_e32 v127, 0xffff0000, v47
	v_pk_mul_f32 v[128:129], v[112:113], v[112:113]
	v_pk_fma_f32 v[128:129], v[114:115], v[114:115], v[128:129]
	v_pk_fma_f32 v[128:129], v[116:117], v[116:117], v[128:129]
	v_pk_fma_f32 v[128:129], v[118:119], v[118:119], v[128:129]
	v_pk_fma_f32 v[128:129], v[120:121], v[120:121], v[128:129]
	v_pk_fma_f32 v[128:129], v[122:123], v[122:123], v[128:129]
	v_pk_fma_f32 v[128:129], v[124:125], v[124:125], v[128:129]
	v_pk_fma_f32 v[128:129], v[126:127], v[126:127], v[128:129]
	v_add_f32_e32 v128, v128, v129
	s_nop 1
	v_add_f32_dpp v128, v128, v128 quad_perm:[1,0,3,2] row_mask:0xf bank_mask:0xf
	s_nop 1
	v_add_f32_dpp v128, v128, v128 quad_perm:[2,3,0,1] row_mask:0xf bank_mask:0xf
	s_nop 1
	v_add_f32_dpp v128, v128, v128 row_half_mirror row_mask:0xf bank_mask:0xf
	s_nop 1
	v_add_f32_dpp v128, v128, v128 row_mirror row_mask:0xf bank_mask:0xf
	s_nop 1
	v_readlane_b32 s6, v128, 0
	v_readlane_b32 s7, v128, 16
	v_readlane_b32 s8, v128, 32
	v_readlane_b32 s9, v128, 48
	s_nop 1
	v_mov_b32_e32 v130, s6
	v_add_f32_e32 v130, s7, v130
	v_add_f32_e32 v130, s8, v130
	v_add_f32_e32 v130, s9, v130
	v_fmamk_f32 v130, v130, 0x3a800000, v207
	v_rsq_f32_e32 v130, v130
	s_add_i32 s20, s60, 2048
	s_lshl_b32 s20, s20, 12
	s_mov_b32 s21, 0
	v_lshl_add_u64 v[134:135], v[28:29], 0, s[20:21]
	v_pk_mul_f32 v[112:113], v[112:113], v[130:131] op_sel_hi:[1,0]
	v_pk_mul_f32 v[114:115], v[114:115], v[130:131] op_sel_hi:[1,0]
	v_pk_mul_f32 v[116:117], v[116:117], v[130:131] op_sel_hi:[1,0]
	v_pk_mul_f32 v[118:119], v[118:119], v[130:131] op_sel_hi:[1,0]
	v_pk_mul_f32 v[120:121], v[120:121], v[130:131] op_sel_hi:[1,0]
	v_pk_mul_f32 v[122:123], v[122:123], v[130:131] op_sel_hi:[1,0]
	v_pk_mul_f32 v[124:125], v[124:125], v[130:131] op_sel_hi:[1,0]
	v_pk_mul_f32 v[126:127], v[126:127], v[130:131] op_sel_hi:[1,0]
	v_pk_mul_f32 v[112:113], v[112:113], v[6:7]
	v_pk_mul_f32 v[114:115], v[114:115], v[8:9]
	v_pk_mul_f32 v[116:117], v[116:117], v[2:3]
	v_pk_mul_f32 v[118:119], v[118:119], v[4:5]
	v_pk_mul_f32 v[120:121], v[120:121], v[14:15]
	v_pk_mul_f32 v[122:123], v[122:123], v[16:17]
	v_pk_mul_f32 v[124:125], v[124:125], v[10:11]
; __device__ __forceinline__ float bf_lo(unsigned w) { return __uint_as_float(w << 16); }
; __device__ __forceinline__ float bf_hi(unsigned w) { return __uint_as_float(w & 0xffff0000u); }
; __global__ void __launch_bounds__(NWAVES * 64, 2) trunk_fwd(Args args) {
;     ...
;                 for (int k = 0; k < 2; ++k) { float* op = out + (size_t)(row0 + k * NGW) * DM + lane * 8;
;                     const f32x4 a0 = {bf_lo(h0[k].x), bf_hi(h0[k].x), bf_lo(h0[k].y), bf_hi(h0[k].y)}, a1 = {bf_lo(h0[k].z), bf_hi(h0[k].z), bf_lo(h0[k].w), bf_hi(h0[k].w)};
;                     const f32x4 a2 = {bf_lo(h1[k].x), bf_hi(h1[k].x), bf_lo(h1[k].y), bf_hi(h1[k].y)}, a3 = {bf_lo(h1[k].z), bf_hi(h1[k].z), bf_lo(h1[k].w), bf_hi(h1[k].w)};
;                     float sq = ((a0[0] * a0[0] + a0[1] * a0[1]) + (a0[2] * a0[2] + a0[3] * a0[3])) + ((a1[0] * a1[0] + a1[1] * a1[1]) + (a1[2] * a1[2] + a1[3] * a1[3]))
;                              + ((a2[0] * a2[0] + a2[1] * a2[1]) + (a2[2] * a2[2] + a2[3] * a2[3])) + ((a3[0] * a3[0] + a3[1] * a3[1]) + (a3[2] * a3[2] + a3[3] * a3[3]));
;                     const float r = __builtin_amdgcn_rsqf(wave_sum(sq) * (1.f / DM) + EPS);
;                     *(f32x4*)(op) = a0 * r * g0; *(f32x4*)(op + 4) = a1 * r * g1; *(f32x4*)(op + 512) = a2 * r * g2; *(f32x4*)(op + 516) = a3 * r * g3; }
	v_pk_mul_f32 v[126:127], v[126:127], v[12:13]
	global_store_dwordx4 v[134:135], v[112:115], off nt
	global_store_dwordx4 v[134:135], v[116:119], off offset:16 nt
	global_store_dwordx4 v[134:135], v[120:123], off offset:2048 nt
	global_store_dwordx4 v[134:135], v[124:127], off offset:2064 nt
	v_lshlrev_b32_e32 v96, 16, v48
	v_and_b32_e32 v97, 0xffff0000, v48
	v_lshlrev_b32_e32 v98, 16, v49
	v_and_b32_e32 v99, 0xffff0000, v49
	v_lshlrev_b32_e32 v100, 16, v50
	v_and_b32_e32 v101, 0xffff0000, v50
	v_lshlrev_b32_e32 v102, 16, v51
	v_and_b32_e32 v103, 0xffff0000, v51
	v_lshlrev_b32_e32 v104, 16, v52
	v_and_b32_e32 v105, 0xffff0000, v52
	v_lshlrev_b32_e32 v106, 16, v53
	v_and_b32_e32 v107, 0xffff0000, v53
	v_lshlrev_b32_e32 v108, 16, v54
	v_and_b32_e32 v109, 0xffff0000, v54
	v_lshlrev_b32_e32 v110, 16, v55
	v_and_b32_e32 v111, 0xffff0000, v55
	v_pk_mul_f32 v[128:129], v[96:97], v[96:97]
	v_pk_fma_f32 v[128:129], v[98:99], v[98:99], v[128:129]
	v_pk_fma_f32 v[128:129], v[100:101], v[100:101], v[128:129]
	v_pk_fma_f32 v[128:129], v[102:103], v[102:103], v[128:129]
	v_pk_fma_f32 v[128:129], v[104:105], v[104:105], v[128:129]
	v_pk_fma_f32 v[128:129], v[106:107], v[106:107], v[128:129]
	v_pk_fma_f32 v[128:129], v[108:109], v[108:109], v[128:129]
	v_pk_fma_f32 v[128:129], v[110:111], v[110:111], v[128:129]
	v_add_f32_e32 v128, v128, v129
	s_nop 1
	v_add_f32_dpp v128, v128, v128 quad_perm:[1,0,3,2] row_mask:0xf bank_mask:0xf
	s_nop 1
	v_add_f32_dpp v128, v128, v128 quad_perm:[2,3,0,1] row_mask:0xf bank_mask:0xf
	s_nop 1
	v_add_f32_dpp v128, v128, v128 row_half_mirror row_mask:0xf bank_mask:0xf
	s_nop 1
	v_add_f32_dpp v128, v128, v128 row_mirror row_mask:0xf bank_mask:0xf
	s_nop 1
	v_readlane_b32 s6, v128, 0
	v_readlane_b32 s7, v128, 16
	v_readlane_b32 s8, v128, 32
	v_readlane_b32 s9, v128, 48
	s_nop 1
	v_mov_b32_e32 v130, s6
	v_add_f32_e32 v130, s7, v130
	v_add_f32_e32 v130, s8, v130
	v_add_f32_e32 v130, s9, v130
	v_fmamk_f32 v130, v130, 0x3a800000, v207
	v_rsq_f32_e32 v130, v130
	s_add_i32 s20, s60, 4096
	s_lshl_b32 s20, s20, 12
	s_mov_b32 s21, 0
	v_lshl_add_u64 v[134:135], v[28:29], 0, s[20:21]
	v_pk_mul_f32 v[96:97], v[96:97], v[130:131] op_sel_hi:[1,0]
	v_pk_mul_f32 v[98:99], v[98:99], v[130:131] op_sel_hi:[1,0]
	v_pk_mul_f32 v[100:101], v[100:101], v[130:131] op_sel_hi:[1,0]
	v_pk_mul_f32 v[102:103], v[102:103], v[130:131] op_sel_hi:[1,0]
	v_pk_mul_f32 v[104:105], v[104:105], v[130:131] op_sel_hi:[1,0]
	v_pk_mul_f32 v[106:107], v[106:107], v[130:131] op_sel_hi:[1,0]
	v_pk_mul_f32 v[108:109], v[108:109], v[130:131] op_sel_hi:[1,0]
	v_pk_mul_f32 v[110:111], v[110:111], v[130:131] op_sel_hi:[1,0]
	v_pk_mul_f32 v[96:97], v[96:97], v[6:7]
	v_pk_mul_f32 v[98:99], v[98:99], v[8:9]
	v_pk_mul_f32 v[100:101], v[100:101], v[2:3]
	v_pk_mul_f32 v[102:103], v[102:103], v[4:5]
	v_pk_mul_f32 v[104:105], v[104:105], v[14:15]
	v_pk_mul_f32 v[106:107], v[106:107], v[16:17]
	v_pk_mul_f32 v[108:109], v[108:109], v[10:11]
	v_pk_mul_f32 v[110:111], v[110:111], v[12:13]
	global_store_dwordx4 v[134:135], v[96:99], off nt
	global_store_dwordx4 v[134:135], v[100:103], off offset:16 nt
	global_store_dwordx4 v[134:135], v[104:107], off offset:2048 nt
	global_store_dwordx4 v[134:135], v[108:111], off offset:2064 nt
	v_lshlrev_b32_e32 v112, 16, v56
	v_and_b32_e32 v113, 0xffff0000, v56
	v_lshlrev_b32_e32 v114, 16, v57
	v_and_b32_e32 v115, 0xffff0000, v57
	v_lshlrev_b32_e32 v116, 16, v58
	v_and_b32_e32 v117, 0xffff0000, v58
	v_lshlrev_b32_e32 v118, 16, v59
	v_and_b32_e32 v119, 0xffff0000, v59
	v_lshlrev_b32_e32 v120, 16, v60
	v_and_b32_e32 v121, 0xffff0000, v60
	v_lshlrev_b32_e32 v122, 16, v61
	v_and_b32_e32 v123, 0xffff0000, v61
	v_lshlrev_b32_e32 v124, 16, v62
	v_and_b32_e32 v125, 0xffff0000, v62
	v_lshlrev_b32_e32 v126, 16, v63
	v_and_b32_e32 v127, 0xffff0000, v63
	v_pk_mul_f32 v[128:129], v[112:113], v[112:113]
	v_pk_fma_f32 v[128:129], v[114:115], v[114:115], v[128:129]
	v_pk_fma_f32 v[128:129], v[116:117], v[116:117], v[128:129]
	v_pk_fma_f32 v[128:129], v[118:119], v[118:119], v[128:129]
	v_pk_fma_f32 v[128:129], v[120:121], v[120:121], v[128:129]
	v_pk_fma_f32 v[128:129], v[122:123], v[122:123], v[128:129]
	v_pk_fma_f32 v[128:129], v[124:125], v[124:125], v[128:129]
	v_pk_fma_f32 v[128:129], v[126:127], v[126:127], v[128:129]
	v_add_f32_e32 v128, v128, v129
	s_nop 1
	v_add_f32_dpp v128, v128, v128 quad_perm:[1,0,3,2] row_mask:0xf bank_mask:0xf
	s_nop 1
	v_add_f32_dpp v128, v128, v128 quad_perm:[2,3,0,1] row_mask:0xf bank_mask:0xf
	s_nop 1
	v_add_f32_dpp v128, v128, v128 row_half_mirror row_mask:0xf bank_mask:0xf
	s_nop 1
	v_add_f32_dpp v128, v128, v128 row_mirror row_mask:0xf bank_mask:0xf
	s_nop 1
	v_readlane_b32 s6, v128, 0
	v_readlane_b32 s7, v128, 16
	v_readlane_b32 s8, v128, 32
	v_readlane_b32 s9, v128, 48
	s_nop 1
	v_mov_b32_e32 v130, s6
	v_add_f32_e32 v130, s7, v130
	v_add_f32_e32 v130, s8, v130
	v_add_f32_e32 v130, s9, v130
	v_fmamk_f32 v130, v130, 0x3a800000, v207
	v_rsq_f32_e32 v130, v130
	s_add_i32 s20, s60, 6144
	s_lshl_b32 s20, s20, 12
	s_mov_b32 s21, 0
	v_lshl_add_u64 v[134:135], v[28:29], 0, s[20:21]
	v_pk_mul_f32 v[112:113], v[112:113], v[130:131] op_sel_hi:[1,0]
	v_pk_mul_f32 v[114:115], v[114:115], v[130:131] op_sel_hi:[1,0]
	v_pk_mul_f32 v[116:117], v[116:117], v[130:131] op_sel_hi:[1,0]
	v_pk_mul_f32 v[118:119], v[118:119], v[130:131] op_sel_hi:[1,0]
	v_pk_mul_f32 v[120:121], v[120:121], v[130:131] op_sel_hi:[1,0]
	v_pk_mul_f32 v[122:123], v[122:123], v[130:131] op_sel_hi:[1,0]
	v_pk_mul_f32 v[124:125], v[124:125], v[130:131] op_sel_hi:[1,0]
	v_pk_mul_f32 v[126:127], v[126:127], v[130:131] op_sel_hi:[1,0]
	v_pk_mul_f32 v[112:113], v[112:113], v[6:7]
	v_pk_mul_f32 v[114:115], v[114:115], v[8:9]
	v_pk_mul_f32 v[116:117], v[116:117], v[2:3]
	v_pk_mul_f32 v[118:119], v[118:119], v[4:5]
	v_pk_mul_f32 v[120:121], v[120:121], v[14:15]
	v_pk_mul_f32 v[122:123], v[122:123], v[16:17]
	v_pk_mul_f32 v[124:125], v[124:125], v[10:11]
	v_pk_mul_f32 v[126:127], v[126:127], v[12:13]
	global_store_dwordx4 v[134:135], v[112:115], off nt
	global_store_dwordx4 v[134:135], v[116:119], off offset:16 nt
	global_store_dwordx4 v[134:135], v[120:123], off offset:2048 nt
	global_store_dwordx4 v[134:135], v[124:127], off offset:2064 nt
	s_add_i32 s22, s60, 0x4000
	s_cmp_lt_u32 s22, 0x10000
	s_cselect_b32 s24, 1, 0
	s_cbranch_scc0 .Lfin_skipA
; __global__ void __launch_bounds__(NWAVES * 64, 2) trunk_fwd(Args args) {
;     ...
;             for (int row0 = gw; row0 < M; row0 += 2 * NGW) {
;                 v4u h0[2], h1[2];
; #pragma unroll
;                 for (int k = 0; k < 2; ++k) { const bf16* hp = HB + (size_t)(row0 + k * NGW) * DM + lane * 8; h0[k] = *(const v4u*)(hp); h1[k] = *(const v4u*)(hp + 512); }
	s_add_i32 s20, s22, 0
	s_lshl_b32 s20, s20, 11
	s_mov_b32 s21, 0
	v_lshl_add_u64 v[132:133], v[26:27], 0, s[20:21]
	global_load_dwordx4 v[32:35], v[132:133], off nt
	global_load_dwordx4 v[36:39], v[132:133], off offset:1024 nt
	s_add_i32 s20, s22, 2048
	s_lshl_b32 s20, s20, 11
	s_mov_b32 s21, 0
	v_lshl_add_u64 v[132:133], v[26:27], 0, s[20:21]
	global_load_dwordx4 v[40:43], v[132:133], off nt
	global_load_dwordx4 v[44:47], v[132:133], off offset:1024 nt
	s_add_i32 s20, s22, 4096
	s_lshl_b32 s20, s20, 11
	s_mov_b32 s21, 0
	v_lshl_add_u64 v[132:133], v[26:27], 0, s[20:21]
	global_load_dwordx4 v[48:51], v[132:133], off nt
	global_load_dwordx4 v[52:55], v[132:133], off offset:1024 nt
	s_add_i32 s20, s22, 6144
	s_lshl_b32 s20, s20, 11
	s_mov_b32 s21, 0
	v_lshl_add_u64 v[132:133], v[26:27], 0, s[20:21]
	global_load_dwordx4 v[56:59], v[132:133], off nt
	global_load_dwordx4 v[60:63], v[132:133], off offset:1024 nt

; __device__ __forceinline__ float bf_lo(unsigned w) { return __uint_as_float(w << 16); }
; __device__ __forceinline__ float bf_hi(unsigned w) { return __uint_as_float(w & 0xffff0000u); }
; __global__ void __launch_bounds__(NWAVES * 64, 2) trunk_fwd(Args args) {
;     ...
;             for (int row0 = gw; row0 < M; row0 += 2 * NGW) {
;                 v4u h0[2], h1[2];
; #pragma unroll
;                 for (int k = 0; k < 2; ++k) { const bf16* hp = HB + (size_t)(row0 + k * NGW) * DM + lane * 8; h0[k] = *(const v4u*)(hp); h1[k] = *(const v4u*)(hp + 512); }
; #pragma unroll
;                 for (int k = 0; k < 2; ++k) { float* op = out + (size_t)(row0 + k * NGW) * DM + lane * 8;
;                     const f32x4 a0 = {bf_lo(h0[k].x), bf_hi(h0[k].x), bf_lo(h0[k].y), bf_hi(h0[k].y)}, a1 = {bf_lo(h0[k].z), bf_hi(h0[k].z), bf_lo(h0[k].w), bf_hi(h0[k].w)};
;                     const f32x4 a2 = {bf_lo(h1[k].x), bf_hi(h1[k].x), bf_lo(h1[k].y), bf_hi(h1[k].y)}, a3 = {bf_lo(h1[k].z), bf_hi(h1[k].z), bf_lo(h1[k].w), bf_hi(h1[k].w)};
;                     float sq = ((a0[0] * a0[0] + a0[1] * a0[1]) + (a0[2] * a0[2] + a0[3] * a0[3])) + ((a1[0] * a1[0] + a1[1] * a1[1]) + (a1[2] * a1[2] + a1[3] * a1[3]))
;                              + ((a2[0] * a2[0] + a2[1] * a2[1]) + (a2[2] * a2[2] + a2[3] * a2[3])) + ((a3[0] * a3[0] + a3[1] * a3[1]) + (a3[2] * a3[2] + a3[3] * a3[3]));
;                     const float r = __builtin_amdgcn_rsqf(wave_sum(sq) * (1.f / DM) + EPS);
;                     *(f32x4*)(op) = a0 * r * g0; *(f32x4*)(op + 4) = a1 * r * g1; *(f32x4*)(op + 512) = a2 * r * g2; *(f32x4*)(op + 516) = a3 * r * g3; }
.Lfin_wbd:
	s_add_i32 s25, s60, 0x2000
	v_lshlrev_b32_e32 v96, 16, v64
	v_and_b32_e32 v97, 0xffff0000, v64
	v_lshlrev_b32_e32 v98, 16, v65
	v_and_b32_e32 v99, 0xffff0000, v65
	v_lshlrev_b32_e32 v100, 16, v66
	v_and_b32_e32 v101, 0xffff0000, v66
	v_lshlrev_b32_e32 v102, 16, v67
	v_and_b32_e32 v103, 0xffff0000, v67
	v_lshlrev_b32_e32 v104, 16, v68
	v_and_b32_e32 v105, 0xffff0000, v68
	v_lshlrev_b32_e32 v106, 16, v69
	v_and_b32_e32 v107, 0xffff0000, v69
	v_lshlrev_b32_e32 v108, 16, v70
	v_and_b32_e32 v109, 0xffff0000, v70
	v_lshlrev_b32_e32 v110, 16, v71
	v_and_b32_e32 v111, 0xffff0000, v71
	v_pk_mul_f32 v[128:129], v[96:97], v[96:97]
	v_pk_fma_f32 v[128:129], v[98:99], v[98:99], v[128:129]
	v_pk_fma_f32 v[128:129], v[100:101], v[100:101], v[128:129]
	v_pk_fma_f32 v[128:129], v[102:103], v[102:103], v[128:129]
	v_pk_fma_f32 v[128:129], v[104:105], v[104:105], v[128:129]
	v_pk_fma_f32 v[128:129], v[106:107], v[106:107], v[128:129]
	v_pk_fma_f32 v[128:129], v[108:109], v[108:109], v[128:129]
	v_pk_fma_f32 v[128:129], v[110:111], v[110:111], v[128:129]
	v_add_f32_e32 v128, v128, v129
	s_nop 1
	v_add_f32_dpp v128, v128, v128 quad_perm:[1,0,3,2] row_mask:0xf bank_mask:0xf
	s_nop 1
	v_add_f32_dpp v128, v128, v128 quad_perm:[2,3,0,1] row_mask:0xf bank_mask:0xf
	s_nop 1
	v_add_f32_dpp v128, v128, v128 row_half_mirror row_mask:0xf bank_mask:0xf
	s_nop 1
	v_add_f32_dpp v128, v128, v128 row_mirror row_mask:0xf bank_mask:0xf
	s_nop 1
	v_readlane_b32 s6, v128, 0
	v_readlane_b32 s7, v128, 16
	v_readlane_b32 s8, v128, 32
	v_readlane_b32 s9, v128, 48
	s_nop 1
	v_mov_b32_e32 v130, s6
	v_add_f32_e32 v130, s7, v130
	v_add_f32_e32 v130, s8, v130
	v_add_f32_e32 v130, s9, v130
	v_fmamk_f32 v130, v130, 0x3a800000, v207
	v_rsq_f32_e32 v130, v130
	s_add_i32 s20, s25, 0
	s_lshl_b32 s20, s20, 12
	s_mov_b32 s21, 0
	v_lshl_add_u64 v[134:135], v[28:29], 0, s[20:21]
	v_pk_mul_f32 v[96:97], v[96:97], v[130:131] op_sel_hi:[1,0]
	v_pk_mul_f32 v[98:99], v[98:99], v[130:131] op_sel_hi:[1,0]
	v_pk_mul_f32 v[100:101], v[100:101], v[130:131] op_sel_hi:[1,0]
	v_pk_mul_f32 v[102:103], v[102:103], v[130:131] op_sel_hi:[1,0]
	v_pk_mul_f32 v[104:105], v[104:105], v[130:131] op_sel_hi:[1,0]
	v_pk_mul_f32 v[106:107], v[106:107], v[130:131] op_sel_hi:[1,0]
	v_pk_mul_f32 v[108:109], v[108:109], v[130:131] op_sel_hi:[1,0]
	v_pk_mul_f32 v[110:111], v[110:111], v[130:131] op_sel_hi:[1,0]
	v_pk_mul_f32 v[96:97], v[96:97], v[6:7]
	v_pk_mul_f32 v[98:99], v[98:99], v[8:9]
	v_pk_mul_f32 v[100:101], v[100:101], v[2:3]
	v_pk_mul_f32 v[102:103], v[102:103], v[4:5]
	v_pk_mul_f32 v[104:105], v[104:105], v[14:15]
	v_pk_mul_f32 v[106:107], v[106:107], v[16:17]
	v_pk_mul_f32 v[108:109], v[108:109], v[10:11]
	v_pk_mul_f32 v[110:111], v[110:111], v[12:13]
	global_store_dwordx4 v[134:135], v[96:99], off nt
	global_store_dwordx4 v[134:135], v[100:103], off offset:16 nt
	global_store_dwordx4 v[134:135], v[104:107], off offset:2048 nt
	global_store_dwordx4 v[134:135], v[108:111], off offset:2064 nt
	v_lshlrev_b32_e32 v112, 16, v72
	v_and_b32_e32 v113, 0xffff0000, v72
	v_lshlrev_b32_e32 v114, 16, v73
	v_and_b32_e32 v115, 0xffff0000, v73
	v_lshlrev_b32_e32 v116, 16, v74
	v_and_b32_e32 v117, 0xffff0000, v74
	v_lshlrev_b32_e32 v118, 16, v75
	v_and_b32_e32 v119, 0xffff0000, v75
	v_lshlrev_b32_e32 v120, 16, v76
	v_and_b32_e32 v121, 0xffff0000, v76
	v_lshlrev_b32_e32 v122, 16, v77
	v_and_b32_e32 v123, 0xffff0000, v77
	v_lshlrev_b32_e32 v124, 16, v78
	v_and_b32_e32 v125, 0xffff0000, v78
	v_lshlrev_b32_e32 v126, 16, v79
	v_and_b32_e32 v127, 0xffff0000, v79
	v_pk_mul_f32 v[128:129], v[112:113], v[112:113]
	v_pk_fma_f32 v[128:129], v[114:115], v[114:115], v[128:129]
	v_pk_fma_f32 v[128:129], v[116:117], v[116:117], v[128:129]
	v_pk_fma_f32 v[128:129], v[118:119], v[118:119], v[128:129]
	v_pk_fma_f32 v[128:129], v[120:121], v[120:121], v[128:129]
	v_pk_fma_f32 v[128:129], v[122:123], v[122:123], v[128:129]
	v_pk_fma_f32 v[128:129], v[124:125], v[124:125], v[128:129]
	v_pk_fma_f32 v[128:129], v[126:127], v[126:127], v[128:129]
	v_add_f32_e32 v128, v128, v129
	s_nop 1
	v_add_f32_dpp v128, v128, v128 quad_perm:[1,0,3,2] row_mask:0xf bank_mask:0xf
	s_nop 1
	v_add_f32_dpp v128, v128, v128 quad_perm:[2,3,0,1] row_mask:0xf bank_mask:0xf
	s_nop 1
	v_add_f32_dpp v128, v128, v128 row_half_mirror row_mask:0xf bank_mask:0xf
	s_nop 1
	v_add_f32_dpp v128, v128, v128 row_mirror row_mask:0xf bank_mask:0xf
	s_nop 1
	v_readlane_b32 s6, v128, 0
	v_readlane_b32 s7, v128, 16
	v_readlane_b32 s8, v128, 32
	v_readlane_b32 s9, v128, 48
	s_nop 1
	v_mov_b32_e32 v130, s6
	v_add_f32_e32 v130, s7, v130
	v_add_f32_e32 v130, s8, v130
	v_add_f32_e32 v130, s9, v130
	v_fmamk_f32 v130, v130, 0x3a800000, v207
	v_rsq_f32_e32 v130, v130
	s_add_i32 s20, s25, 2048
	s_lshl_b32 s20, s20, 12
	s_mov_b32 s21, 0
	v_lshl_add_u64 v[134:135], v[28:29], 0, s[20:21]
	v_pk_mul_f32 v[112:113], v[112:113], v[130:131] op_sel_hi:[1,0]
	v_pk_mul_f32 v[114:115], v[114:115], v[130:131] op_sel_hi:[1,0]
	v_pk_mul_f32 v[116:117], v[116:117], v[130:131] op_sel_hi:[1,0]
	v_pk_mul_f32 v[118:119], v[118:119], v[130:131] op_sel_hi:[1,0]
	v_pk_mul_f32 v[120:121], v[120:121], v[130:131] op_sel_hi:[1,0]
	v_pk_mul_f32 v[122:123], v[122:123], v[130:131] op_sel_hi:[1,0]
	v_pk_mul_f32 v[124:125], v[124:125], v[130:131] op_sel_hi:[1,0]
	v_pk_mul_f32 v[126:127], v[126:127], v[130:131] op_sel_hi:[1,0]
	v_pk_mul_f32 v[112:113], v[112:113], v[6:7]
	v_pk_mul_f32 v[114:115], v[114:115], v[8:9]
	v_pk_mul_f32 v[116:117], v[116:117], v[2:3]
	v_pk_mul_f32 v[118:119], v[118:119], v[4:5]
	v_pk_mul_f32 v[120:121], v[120:121], v[14:15]
	v_pk_mul_f32 v[122:123], v[122:123], v[16:17]
	v_pk_mul_f32 v[124:125], v[124:125], v[10:11]
; __device__ __forceinline__ float bf_lo(unsigned w) { return __uint_as_float(w << 16); }
; __device__ __forceinline__ float bf_hi(unsigned w) { return __uint_as_float(w & 0xffff0000u); }
; __global__ void __launch_bounds__(NWAVES * 64, 2) trunk_fwd(Args args) {
;     ...
;             for (int row0 = gw; row0 < M; row0 += 2 * NGW) {
;                 v4u h0[2], h1[2];
; #pragma unroll
;                 for (int k = 0; k < 2; ++k) { const bf16* hp = HB + (size_t)(row0 + k * NGW) * DM + lane * 8; h0[k] = *(const v4u*)(hp); h1[k] = *(const v4u*)(hp + 512); }
; #pragma unroll
;                 for (int k = 0; k < 2; ++k) { float* op = out + (size_t)(row0 + k * NGW) * DM + lane * 8;
;                     const f32x4 a0 = {bf_lo(h0[k].x), bf_hi(h0[k].x), bf_lo(h0[k].y), bf_hi(h0[k].y)}, a1 = {bf_lo(h0[k].z), bf_hi(h0[k].z), bf_lo(h0[k].w), bf_hi(h0[k].w)};
;                     const f32x4 a2 = {bf_lo(h1[k].x), bf_hi(h1[k].x), bf_lo(h1[k].y), bf_hi(h1[k].y)}, a3 = {bf_lo(h1[k].z), bf_hi(h1[k].z), bf_lo(h1[k].w), bf_hi(h1[k].w)};
;                     float sq = ((a0[0] * a0[0] + a0[1] * a0[1]) + (a0[2] * a0[2] + a0[3] * a0[3])) + ((a1[0] * a1[0] + a1[1] * a1[1]) + (a1[2] * a1[2] + a1[3] * a1[3]))
;                              + ((a2[0] * a2[0] + a2[1] * a2[1]) + (a2[2] * a2[2] + a2[3] * a2[3])) + ((a3[0] * a3[0] + a3[1] * a3[1]) + (a3[2] * a3[2] + a3[3] * a3[3]));
;                     const float r = __builtin_amdgcn_rsqf(wave_sum(sq) * (1.f / DM) + EPS);
;                     *(f32x4*)(op) = a0 * r * g0; *(f32x4*)(op + 4) = a1 * r * g1; *(f32x4*)(op + 512) = a2 * r * g2; *(f32x4*)(op + 516) = a3 * r * g3; }
	v_pk_mul_f32 v[126:127], v[126:127], v[12:13]
	global_store_dwordx4 v[134:135], v[112:115], off nt
	global_store_dwordx4 v[134:135], v[116:119], off offset:16 nt
	global_store_dwordx4 v[134:135], v[120:123], off offset:2048 nt
	global_store_dwordx4 v[134:135], v[124:127], off offset:2064 nt
	v_lshlrev_b32_e32 v96, 16, v80
	v_and_b32_e32 v97, 0xffff0000, v80
	v_lshlrev_b32_e32 v98, 16, v81
	v_and_b32_e32 v99, 0xffff0000, v81
	v_lshlrev_b32_e32 v100, 16, v82
	v_and_b32_e32 v101, 0xffff0000, v82
	v_lshlrev_b32_e32 v102, 16, v83
	v_and_b32_e32 v103, 0xffff0000, v83
	v_lshlrev_b32_e32 v104, 16, v84
	v_and_b32_e32 v105, 0xffff0000, v84
	v_lshlrev_b32_e32 v106, 16, v85
	v_and_b32_e32 v107, 0xffff0000, v85
	v_lshlrev_b32_e32 v108, 16, v86
	v_and_b32_e32 v109, 0xffff0000, v86
	v_lshlrev_b32_e32 v110, 16, v87
	v_and_b32_e32 v111, 0xffff0000, v87
	v_pk_mul_f32 v[128:129], v[96:97], v[96:97]
	v_pk_fma_f32 v[128:129], v[98:99], v[98:99], v[128:129]
	v_pk_fma_f32 v[128:129], v[100:101], v[100:101], v[128:129]
	v_pk_fma_f32 v[128:129], v[102:103], v[102:103], v[128:129]
	v_pk_fma_f32 v[128:129], v[104:105], v[104:105], v[128:129]
	v_pk_fma_f32 v[128:129], v[106:107], v[106:107], v[128:129]
	v_pk_fma_f32 v[128:129], v[108:109], v[108:109], v[128:129]
	v_pk_fma_f32 v[128:129], v[110:111], v[110:111], v[128:129]
	v_add_f32_e32 v128, v128, v129
	s_nop 1
	v_add_f32_dpp v128, v128, v128 quad_perm:[1,0,3,2] row_mask:0xf bank_mask:0xf
	s_nop 1
	v_add_f32_dpp v128, v128, v128 quad_perm:[2,3,0,1] row_mask:0xf bank_mask:0xf
	s_nop 1
	v_add_f32_dpp v128, v128, v128 row_half_mirror row_mask:0xf bank_mask:0xf
	s_nop 1
	v_add_f32_dpp v128, v128, v128 row_mirror row_mask:0xf bank_mask:0xf
	s_nop 1
	v_readlane_b32 s6, v128, 0
	v_readlane_b32 s7, v128, 16
	v_readlane_b32 s8, v128, 32
	v_readlane_b32 s9, v128, 48
	s_nop 1
	v_mov_b32_e32 v130, s6
	v_add_f32_e32 v130, s7, v130
	v_add_f32_e32 v130, s8, v130
	v_add_f32_e32 v130, s9, v130
	v_fmamk_f32 v130, v130, 0x3a800000, v207
	v_rsq_f32_e32 v130, v130
	s_add_i32 s20, s25, 4096
	s_lshl_b32 s20, s20, 12
	s_mov_b32 s21, 0
	v_lshl_add_u64 v[134:135], v[28:29], 0, s[20:21]
	v_pk_mul_f32 v[96:97], v[96:97], v[130:131] op_sel_hi:[1,0]
	v_pk_mul_f32 v[98:99], v[98:99], v[130:131] op_sel_hi:[1,0]
	v_pk_mul_f32 v[100:101], v[100:101], v[130:131] op_sel_hi:[1,0]
	v_pk_mul_f32 v[102:103], v[102:103], v[130:131] op_sel_hi:[1,0]
	v_pk_mul_f32 v[104:105], v[104:105], v[130:131] op_sel_hi:[1,0]
	v_pk_mul_f32 v[106:107], v[106:107], v[130:131] op_sel_hi:[1,0]
	v_pk_mul_f32 v[108:109], v[108:109], v[130:131] op_sel_hi:[1,0]
	v_pk_mul_f32 v[110:111], v[110:111], v[130:131] op_sel_hi:[1,0]
	v_pk_mul_f32 v[96:97], v[96:97], v[6:7]
	v_pk_mul_f32 v[98:99], v[98:99], v[8:9]
	v_pk_mul_f32 v[100:101], v[100:101], v[2:3]
	v_pk_mul_f32 v[102:103], v[102:103], v[4:5]
	v_pk_mul_f32 v[104:105], v[104:105], v[14:15]
	v_pk_mul_f32 v[106:107], v[106:107], v[16:17]
	v_pk_mul_f32 v[108:109], v[108:109], v[10:11]
	v_pk_mul_f32 v[110:111], v[110:111], v[12:13]
	global_store_dwordx4 v[134:135], v[96:99], off nt
	global_store_dwordx4 v[134:135], v[100:103], off offset:16 nt
	global_store_dwordx4 v[134:135], v[104:107], off offset:2048 nt
	global_store_dwordx4 v[134:135], v[108:111], off offset:2064 nt
	v_lshlrev_b32_e32 v112, 16, v88
	v_and_b32_e32 v113, 0xffff0000, v88
	v_lshlrev_b32_e32 v114, 16, v89
	v_and_b32_e32 v115, 0xffff0000, v89
	v_lshlrev_b32_e32 v116, 16, v90
	v_and_b32_e32 v117, 0xffff0000, v90
	v_lshlrev_b32_e32 v118, 16, v91
	v_and_b32_e32 v119, 0xffff0000, v91
	v_lshlrev_b32_e32 v120, 16, v92
	v_and_b32_e32 v121, 0xffff0000, v92
	v_lshlrev_b32_e32 v122, 16, v93
	v_and_b32_e32 v123, 0xffff0000, v93
	v_lshlrev_b32_e32 v124, 16, v94
	v_and_b32_e32 v125, 0xffff0000, v94
	v_lshlrev_b32_e32 v126, 16, v95
	v_and_b32_e32 v127, 0xffff0000, v95
	v_pk_mul_f32 v[128:129], v[112:113], v[112:113]
	v_pk_fma_f32 v[128:129], v[114:115], v[114:115], v[128:129]
	v_pk_fma_f32 v[128:129], v[116:117], v[116:117], v[128:129]
	v_pk_fma_f32 v[128:129], v[118:119], v[118:119], v[128:129]
	v_pk_fma_f32 v[128:129], v[120:121], v[120:121], v[128:129]
	v_pk_fma_f32 v[128:129], v[122:123], v[122:123], v[128:129]
	v_pk_fma_f32 v[128:129], v[124:125], v[124:125], v[128:129]
	v_pk_fma_f32 v[128:129], v[126:127], v[126:127], v[128:129]
	v_add_f32_e32 v128, v128, v129
	s_nop 1
	v_add_f32_dpp v128, v128, v128 quad_perm:[1,0,3,2] row_mask:0xf bank_mask:0xf
	s_nop 1
	v_add_f32_dpp v128, v128, v128 quad_perm:[2,3,0,1] row_mask:0xf bank_mask:0xf
	s_nop 1
	v_add_f32_dpp v128, v128, v128 row_half_mirror row_mask:0xf bank_mask:0xf
	s_nop 1
	v_add_f32_dpp v128, v128, v128 row_mirror row_mask:0xf bank_mask:0xf
	s_nop 1
	v_readlane_b32 s6, v128, 0
	v_readlane_b32 s7, v128, 16
	v_readlane_b32 s8, v128, 32
	v_readlane_b32 s9, v128, 48
	s_nop 1
	v_mov_b32_e32 v130, s6
	v_add_f32_e32 v130, s7, v130
	v_add_f32_e32 v130, s8, v130
	v_add_f32_e32 v130, s9, v130
	v_fmamk_f32 v130, v130, 0x3a800000, v207
	v_rsq_f32_e32 v130, v130
	s_add_i32 s20, s25, 6144
	s_lshl_b32 s20, s20, 12
	s_mov_b32 s21, 0
	v_lshl_add_u64 v[134:135], v[28:29], 0, s[20:21]
	v_pk_mul_f32 v[112:113], v[112:113], v[130:131] op_sel_hi:[1,0]
	v_pk_mul_f32 v[114:115], v[114:115], v[130:131] op_sel_hi:[1,0]
	v_pk_mul_f32 v[116:117], v[116:117], v[130:131] op_sel_hi:[1,0]
	v_pk_mul_f32 v[118:119], v[118:119], v[130:131] op_sel_hi:[1,0]
	v_pk_mul_f32 v[120:121], v[120:121], v[130:131] op_sel_hi:[1,0]
	v_pk_mul_f32 v[122:123], v[122:123], v[130:131] op_sel_hi:[1,0]
	v_pk_mul_f32 v[124:125], v[124:125], v[130:131] op_sel_hi:[1,0]
	v_pk_mul_f32 v[126:127], v[126:127], v[130:131] op_sel_hi:[1,0]
	v_pk_mul_f32 v[112:113], v[112:113], v[6:7]
	v_pk_mul_f32 v[114:115], v[114:115], v[8:9]
	v_pk_mul_f32 v[116:117], v[116:117], v[2:3]
	v_pk_mul_f32 v[118:119], v[118:119], v[4:5]
	v_pk_mul_f32 v[120:121], v[120:121], v[14:15]
	v_pk_mul_f32 v[122:123], v[122:123], v[16:17]
	v_pk_mul_f32 v[124:125], v[124:125], v[10:11]
	v_pk_mul_f32 v[126:127], v[126:127], v[12:13]
	global_store_dwordx4 v[134:135], v[112:115], off nt
	global_store_dwordx4 v[134:135], v[116:119], off offset:16 nt
	global_store_dwordx4 v[134:135], v[120:123], off offset:2048 nt
	global_store_dwordx4 v[134:135], v[124:127], off offset:2064 nt
	s_add_i32 s22, s60, 0x6000
	s_cmp_lt_u32 s22, 0x10000
	s_cbranch_scc0 .Lfin_skipB
; __global__ void __launch_bounds__(NWAVES * 64, 2) trunk_fwd(Args args) {
;     ...
;                 for (int k = 0; k < 2; ++k) { const bf16* hp = HB + (size_t)(row0 + k * NGW) * DM + lane * 8; h0[k] = *(const v4u*)(hp); h1[k] = *(const v4u*)(hp + 512); }
	s_add_i32 s20, s22, 0
	s_lshl_b32 s20, s20, 11
	s_mov_b32 s21, 0
	v_lshl_add_u64 v[132:133], v[26:27], 0, s[20:21]
	global_load_dwordx4 v[64:67], v[132:133], off nt
	global_load_dwordx4 v[68:71], v[132:133], off offset:1024 nt
	s_add_i32 s20, s22, 2048
	s_lshl_b32 s20, s20, 11
	s_mov_b32 s21, 0
	v_lshl_add_u64 v[132:133], v[26:27], 0, s[20:21]
	global_load_dwordx4 v[72:75], v[132:133], off nt
	global_load_dwordx4 v[76:79], v[132:133], off offset:1024 nt
	s_add_i32 s20, s22, 4096
	s_lshl_b32 s20, s20, 11
	s_mov_b32 s21, 0
	v_lshl_add_u64 v[132:133], v[26:27], 0, s[20:21]
	global_load_dwordx4 v[80:83], v[132:133], off nt
	global_load_dwordx4 v[84:87], v[132:133], off offset:1024 nt
	s_add_i32 s20, s22, 6144
	s_lshl_b32 s20, s20, 11
	s_mov_b32 s21, 0
	v_lshl_add_u64 v[132:133], v[26:27], 0, s[20:21]
	global_load_dwordx4 v[88:91], v[132:133], off nt
	global_load_dwordx4 v[92:95], v[132:133], off offset:1024 nt
